# v103 + differential-attention key loop: loop-head scalar work and next-tile global loads rotated in front of the loop-back barrier (7.11)
# baseline (speedup 1.0000x reference)
.LBB0_554:
	s_sub_i32 s71, s71, 64
	s_addk_i32 s73, 0x4800
	s_add_i32 s72, s72, 1
	s_add_i32 s74, s74, 1
	s_add_i32 s4, s4, -1
	s_add_i32 s98, s71, 64
	s_cmp_gt_i32 s98, s75
	s_cselect_b32 s97, 1, 0
	s_bitcmp1_b32 s72, 0
	s_cselect_b32 s77, 0, 0x4400
	v_add_u32_e32 v96, s77, v235
	s_add_i32 s76, s4, 1
	s_cmp_gt_i32 s76, 0
	s_cselect_b64 s[40:41], -1, 0
	s_waitcnt lgkmcnt(0)
	s_cbranch_scc0 .Ldf_rot_noload
	s_lshl_b32 s98, s4, 14
	s_add_u32 s92, s88, s98
	s_addc_u32 s93, s89, 0
	s_add_u32 s94, s90, s98
	s_addc_u32 s95, s91, 0
	global_load_dwordx4 v[144:147], v246, s[92:93]
	global_load_dwordx4 v[148:151], v246, s[94:95]
	global_load_dwordx4 v[152:155], v245, s[92:93]
	global_load_dwordx4 v[156:159], v245, s[94:95]
.Ldf_rot_noload:
	s_mul_hi_u32 s76, s74, 0xaaaaaaab
	s_lshr_b32 s76, s76, 1
	s_cmpk_eq_i32 s71, 0xff80
	s_barrier
	s_cbranch_scc1 .LBB0_572
	s_cmp_lg_u32 s97, 0
	s_cbranch_scc1 .LBB0_568
	s_branch .Ldf_rot_body

.Ldf_rot_body:
	ds_read_b128 v[92:95], v96
	ds_read_b128 v[88:91], v96 offset:32
	ds_read_b128 v[84:87], v96 offset:64
	ds_read_b128 v[80:83], v96 offset:96
	ds_read_b128 v[120:123], v96 offset:8704
	ds_read_b128 v[116:119], v96 offset:8736
	ds_read_b128 v[112:115], v96 offset:8768
	ds_read_b128 v[208:211], v96 offset:8800
	s_mul_i32 s76, s76, 0xd800
	s_sub_i32 s86, s73, s76
	s_andn2_b64 vcc, exec, s[42:43]
	v_add_u32_e32 v247, s86, v248
	s_cbranch_vccnz .LBB0_560
	ds_read_b128 v[184:187], v247 offset:32
	ds_read_b128 v[180:183], v247 offset:64
	ds_read_b128 v[188:191], v247
	ds_read_b128 v[176:179], v247 offset:96
